# v38 + attention row sums via v_pk_add_f32 (15 fewer VALU per tile iteration)
# baseline (speedup 1.0000x reference)
; #define A_LOAD(t) do { _Pragma("unroll") for (int j_ = 0; j_ < 2; ++j_) { kreg[j_] = *(const u32x4*)(kg + (size_t)(64 * (t) + 32 * j_) * NIN); vreg[j_] = *(const u32x4*)(kg + 512 + (size_t)(64 * (t) + 32 * j_) * NIN); } } while (0)
; #define A_STORE(kbi, vbi) do { _Pragma("unroll") for (int j_ = 0; j_ < 2; ++j_) { *(LAS u32x4*)(lds + A_K0 + (kbi) * KBUF + (skey + 32 * j_) * KSTR + sch * 16) = kreg[j_]; *(LAS u32x4*)(lds + A_V0 + (vbi) * VBUF + (skey + 32 * j_) * VSTR + sch * 16) = vreg[j_]; } } while (0)
; __device__ __forceinline__ void attn_phase(LAS unsigned char* lds, const AttnArgs& a, int tid_in) {
;     ...
;         for (; t < NTM; ++t) {
;             A_PIPE(false, t, vp);
;             A_STORE((t + 1) & 1, vn);
;             if (t + 2 < NT) A_LOAD(t + 2);
;             __syncthreads();
;             vp = (vp == 2) ? 0 : vp + 1; vn = (vn == 2) ? 0 : vn + 1;
;         }
.LBB0_581:
	s_setprio 1
	s_bitcmp1_b32 s4, 0
	s_cselect_b32 s30, 0x4400, 0
	v_add_u32_e32 v0, s30, v224
	ds_read_b128 v[2:5], v0
	ds_read_b128 v[6:9], v0 offset:32
	s_mul_i32 s30, s6, 0x5000
	s_waitcnt lgkmcnt(1)
	v_mfma_f32_32x32x16_bf16 v[128:143], v[2:5], v[144:147], v[96:111]
	ds_read_b128 v[2:5], v0 offset:8704
	ds_read_b128 v[10:13], v0 offset:8736
	s_waitcnt lgkmcnt(1)
	v_mfma_f32_32x32x16_bf16 v[112:127], v[2:5], v[144:147], v[96:111]
	v_mfma_f32_32x32x16_bf16 v[128:143], v[6:9], v[148:151], v[128:143]
	ds_read_b128 v[2:5], v0 offset:64
	ds_read_b128 v[6:9], v0 offset:96
	s_waitcnt lgkmcnt(2)
	v_mfma_f32_32x32x16_bf16 v[112:127], v[10:13], v[148:151], v[112:127]
	s_waitcnt lgkmcnt(1)
	v_mfma_f32_32x32x16_bf16 v[128:143], v[2:5], v[152:155], v[128:143]
	ds_read_b128 v[2:5], v0 offset:8768
	ds_read_b128 v[10:13], v0 offset:8800
	v_add_u32_e32 v0, s30, v225
	s_waitcnt lgkmcnt(1)
	v_mfma_f32_32x32x16_bf16 v[112:127], v[2:5], v[152:155], v[112:127]
	v_mfma_f32_32x32x16_bf16 v[128:143], v[6:9], v[156:159], v[128:143]
	ds_read_b64_tr_b16 v[2:3], v0 offset:34816
	ds_read_b64_tr_b16 v[6:7], v0 offset:34880
	ds_read_b64_tr_b16 v[236:237], v0 offset:34944
	ds_read_b64_tr_b16 v[240:241], v0 offset:35008
	ds_read_b64_tr_b16 v[4:5], v0 offset:37376
	ds_read_b64_tr_b16 v[8:9], v0 offset:37440
	ds_read_b64_tr_b16 v[238:239], v0 offset:37504
	ds_read_b64_tr_b16 v[242:243], v0 offset:37568
	s_waitcnt lgkmcnt(8)
	v_mfma_f32_32x32x16_bf16 v[112:127], v[10:13], v[156:159], v[112:127]
	s_waitcnt lgkmcnt(3)
	v_mfma_f32_32x32x16_bf16 v[64:79], v[188:191], v[2:5], v[64:79]
	ds_read_b64_tr_b16 v[2:3], v0 offset:39936
	ds_read_b64_tr_b16 v[4:5], v0 offset:42496
	v_exp_f32_e32 v128, v128
	v_exp_f32_e32 v129, v129
	v_exp_f32_e32 v130, v130
	s_waitcnt lgkmcnt(4)
	v_mfma_f32_32x32x16_bf16 v[80:95], v[188:191], v[6:9], v[80:95]
	ds_read_b64_tr_b16 v[6:7], v0 offset:40000
	ds_read_b64_tr_b16 v[8:9], v0 offset:42560
	v_exp_f32_e32 v131, v131
	v_exp_f32_e32 v132, v132
	v_exp_f32_e32 v133, v133
	v_pk_add_f32 v[18:19], v[128:129], v[130:131]
	s_waitcnt lgkmcnt(5)
	v_mfma_f32_32x32x16_bf16 v[48:63], v[188:191], v[236:239], v[48:63]
	ds_read_b64_tr_b16 v[10:11], v0 offset:40064
	ds_read_b64_tr_b16 v[12:13], v0 offset:42624
	v_exp_f32_e32 v134, v134
	v_exp_f32_e32 v135, v135
	v_exp_f32_e32 v136, v136
	v_pk_add_f32 v[18:19], v[18:19], v[132:133]
	s_waitcnt lgkmcnt(6)
	v_mfma_f32_32x32x16_bf16 v[32:47], v[188:191], v[240:243], v[32:47]
	ds_read_b64_tr_b16 v[28:29], v0 offset:40128
	ds_read_b64_tr_b16 v[30:31], v0 offset:42688
	v_exp_f32_e32 v137, v137
	v_exp_f32_e32 v138, v138
	v_exp_f32_e32 v139, v139
	v_cvt_pk_bf16_f32 v188, v128, v129
	s_waitcnt lgkmcnt(6)
	v_mfma_f32_32x32x16_bf16 v[64:79], v[184:187], v[2:5], v[64:79]
	ds_read_b64_tr_b16 v[2:3], v0 offset:45056
	ds_read_b64_tr_b16 v[4:5], v0 offset:47616
	v_exp_f32_e32 v140, v140
	v_exp_f32_e32 v141, v141
	v_exp_f32_e32 v142, v142
	v_cvt_pk_bf16_f32 v189, v130, v131
	s_waitcnt lgkmcnt(6)
	v_mfma_f32_32x32x16_bf16 v[80:95], v[184:187], v[6:9], v[80:95]
	ds_read_b64_tr_b16 v[6:7], v0 offset:45120
	ds_read_b64_tr_b16 v[8:9], v0 offset:47680
	v_exp_f32_e32 v143, v143
	v_exp_f32_e32 v112, v112
	v_exp_f32_e32 v113, v113
	v_cvt_pk_bf16_f32 v190, v132, v133
	s_waitcnt lgkmcnt(6)
	v_mfma_f32_32x32x16_bf16 v[48:63], v[184:187], v[10:13], v[48:63]
	ds_read_b64_tr_b16 v[10:11], v0 offset:45184
	ds_read_b64_tr_b16 v[12:13], v0 offset:47744
	v_exp_f32_e32 v114, v114
	v_exp_f32_e32 v115, v115
	v_exp_f32_e32 v116, v116
	v_cvt_pk_bf16_f32 v191, v134, v135
	s_waitcnt lgkmcnt(6)
	v_mfma_f32_32x32x16_bf16 v[32:47], v[184:187], v[28:31], v[32:47]
	ds_read_b64_tr_b16 v[28:29], v0 offset:45248
	ds_read_b64_tr_b16 v[30:31], v0 offset:47808
	s_andn2_b32 s30, 1, s4
	s_mulk_i32 s30, 0x4400
	s_mul_i32 s31, s34, 0x5000
	v_add3_u32 v21, v223, s30, v228
	v_add3_u32 v22, v223, s31, v229
	v_exp_f32_e32 v117, v117
	v_exp_f32_e32 v118, v118
	v_exp_f32_e32 v119, v119
	v_cvt_pk_bf16_f32 v184, v136, v137
	s_waitcnt lgkmcnt(6)
	v_mfma_f32_32x32x16_bf16 v[64:79], v[180:183], v[2:5], v[64:79]
	ds_read_b64_tr_b16 v[2:3], v0 offset:50176
	ds_read_b64_tr_b16 v[4:5], v0 offset:52736
	s_waitcnt vmcnt(3)
	ds_write_b128 v21, v[160:163]
	v_exp_f32_e32 v120, v120
	v_exp_f32_e32 v121, v121
	v_exp_f32_e32 v122, v122
	v_cvt_pk_bf16_f32 v185, v138, v139
	s_waitcnt lgkmcnt(7)
	v_mfma_f32_32x32x16_bf16 v[80:95], v[180:183], v[6:9], v[80:95]
	ds_read_b64_tr_b16 v[6:7], v0 offset:50240
	ds_read_b64_tr_b16 v[8:9], v0 offset:52800
	s_waitcnt vmcnt(2)
	ds_write_b128 v22, v[164:167] offset:34816
	v_exp_f32_e32 v123, v123
	v_exp_f32_e32 v124, v124
	v_exp_f32_e32 v125, v125
	v_cvt_pk_bf16_f32 v186, v140, v141
	s_waitcnt lgkmcnt(8)
	v_mfma_f32_32x32x16_bf16 v[48:63], v[180:183], v[10:13], v[48:63]
	ds_read_b64_tr_b16 v[10:11], v0 offset:50304
	ds_read_b64_tr_b16 v[12:13], v0 offset:52864
	s_waitcnt vmcnt(1)
	ds_write_b128 v21, v[168:171] offset:8704
	v_exp_f32_e32 v126, v126
	v_exp_f32_e32 v127, v127
	v_cvt_pk_bf16_f32 v187, v142, v143
	v_pk_add_f32 v[18:19], v[18:19], v[134:135]
	v_pk_add_f32 v[18:19], v[18:19], v[136:137]
	s_waitcnt lgkmcnt(9)
	v_mfma_f32_32x32x16_bf16 v[32:47], v[180:183], v[28:31], v[32:47]
	ds_read_b64_tr_b16 v[28:29], v0 offset:50368
	ds_read_b64_tr_b16 v[30:31], v0 offset:52928
	s_waitcnt vmcnt(0)
	ds_write_b128 v22, v[172:175] offset:45056
	v_cvt_pk_bf16_f32 v180, v112, v113
	v_cvt_pk_bf16_f32 v181, v114, v115
	v_cvt_pk_bf16_f32 v182, v116, v117
	v_cvt_pk_bf16_f32 v183, v118, v119
	v_pk_add_f32 v[18:19], v[18:19], v[138:139]
	v_pk_add_f32 v[18:19], v[18:19], v[140:141]
	v_pk_add_f32 v[18:19], v[18:19], v[142:143]
	s_waitcnt lgkmcnt(10)
	v_mfma_f32_32x32x16_bf16 v[64:79], v[176:179], v[2:5], v[64:79]
	v_pk_add_f32 v[14:15], v[112:113], v[114:115]
	v_pk_add_f32 v[14:15], v[14:15], v[116:117]
	v_pk_add_f32 v[14:15], v[14:15], v[118:119]
	v_pk_add_f32 v[14:15], v[14:15], v[120:121]
	v_pk_add_f32 v[14:15], v[14:15], v[122:123]
	v_pk_add_f32 v[14:15], v[14:15], v[124:125]
	v_pk_add_f32 v[14:15], v[14:15], v[126:127]
	s_waitcnt lgkmcnt(7)
	v_mfma_f32_32x32x16_bf16 v[80:95], v[176:179], v[6:9], v[80:95]
	v_pk_add_f32 v[18:19], v[18:19], v[14:15]
	v_add_f32_e32 v17, v18, v19
	v_add_f32_e32 v211, v211, v17
	s_add_i32 s30, s4, 2
	s_cmp_ge_i32 s30, s27
	s_cbranch_scc1 .Lattn_u_skipld
	s_sub_i32 s30, s5, 32
	v_mad_u64_u32 v[24:25], s[30:31], s30, v219, v[202:203]
	v_mad_u64_u32 v[26:27], s[30:31], s5, v219, v[202:203]
	global_load_dwordx4 v[160:163], v[24:25], off
	global_load_dwordx4 v[164:167], v[24:25], off offset:1024
	global_load_dwordx4 v[168:171], v[26:27], off
	global_load_dwordx4 v[172:175], v[26:27], off offset:1024
; #define A_LOAD(t) do { _Pragma("unroll") for (int j_ = 0; j_ < 2; ++j_) { kreg[j_] = *(const u32x4*)(kg + (size_t)(64 * (t) + 32 * j_) * NIN); vreg[j_] = *(const u32x4*)(kg + 512 + (size_t)(64 * (t) + 32 * j_) * NIN); } } while (0)
; #define A_STORE(kbi, vbi) do { _Pragma("unroll") for (int j_ = 0; j_ < 2; ++j_) { *(LAS u32x4*)(lds + A_K0 + (kbi) * KBUF + (skey + 32 * j_) * KSTR + sch * 16) = kreg[j_]; *(LAS u32x4*)(lds + A_V0 + (vbi) * VBUF + (skey + 32 * j_) * VSTR + sch * 16) = vreg[j_]; } } while (0)
; __device__ __forceinline__ void attn_phase(LAS unsigned char* lds, const AttnArgs& a, int tid_in) {
;     ...
;         for (; t < NTM; ++t) {
;             A_PIPE(false, t, vp);
;             A_STORE((t + 1) & 1, vn);
;             if (t + 2 < NT) A_LOAD(t + 2);
;             __syncthreads();
;             vp = (vp == 2) ? 0 : vp + 1; vn = (vn == 2) ? 0 : vn + 1;
;         }
.Lattn_u_skipld:
	s_waitcnt lgkmcnt(4)
	v_mfma_f32_32x32x16_bf16 v[48:63], v[176:179], v[10:13], v[48:63]
	s_waitcnt lgkmcnt(1)
	v_mfma_f32_32x32x16_bf16 v[32:47], v[176:179], v[28:31], v[32:47]
	v_cvt_pk_bf16_f32 v176, v120, v121
	v_cvt_pk_bf16_f32 v177, v122, v123
	v_cvt_pk_bf16_f32 v178, v124, v125
	v_cvt_pk_bf16_f32 v179, v126, v127
	s_setprio 0
	s_add_i32 s30, s6, 1
	s_cmp_lg_u32 s6, 2
	s_cselect_b32 s6, s30, 0
	s_add_i32 s30, s34, 1
	s_cmp_lg_u32 s34, 2
	s_cselect_b32 s34, s30, 0
	s_add_i32 s4, s4, 1
	s_add_i32 s5, s5, 64
	s_cmp_eq_u32 s35, s4
	s_waitcnt lgkmcnt(0)
	s_barrier
	s_cbranch_scc0 .LBB0_581
	s_branch .LBB0_584
